# v43 + P2 queue: waves 4-7 touch a 128 KiB chunk of the XCD's x_prompt region after items 16..79 (LLC warm for P3's residual reads; nothing in the P2 tail)
# speedup vs baseline: 1.0001x; 1.0001x over previous
.LBB0_400:
	v_readfirstlane_b32 s98, v0
	s_cmp_lt_u32 s98, 256
	s_cbranch_scc1 .Lmy_x2_skip
	s_cmp_lt_i32 s101, 16
	s_cbranch_scc1 .Lmy_x2_skip
	s_cmp_gt_i32 s101, 79
	s_cbranch_scc1 .Lmy_x2_skip
	v_readlane_b32 s98, v251, 63
	s_and_b32 s98, s98, 7
	s_lshl_b32 s98, s98, 23
	s_sub_i32 s99, s101, 16
	s_lshl_b32 s99, s99, 17
	s_add_u32 s98, s98, s99
	s_add_u32 s98, s76, s98
	s_addc_u32 s99, s77, 0
	v_add_u32_e32 v252, 0xffffff00, v0
	v_lshlrev_b32_e32 v252, 7, v252
	s_nop 1
	global_load_dword v255, v252, s[98:99]
	v_add_u32_e32 v253, 0x8000, v252
	global_load_dword v255, v253, s[98:99]
	v_add_u32_e32 v253, 0x10000, v252
	global_load_dword v255, v253, s[98:99]
	v_add_u32_e32 v253, 0x18000, v252
	global_load_dword v255, v253, s[98:99]
